# M1 load balance: workgroups owning a fifth GLA chunk-state item take no pooling items; their 64 pooling items move to workgroups idle in the last round
# baseline (speedup 1.0000x reference)
; __global__ void __launch_bounds__(512, 2) fwd_kernel(KP kparg) {
;     ...
;         for (int it = c; it < 1056 + 528 + 255; it += G) { const int item = (G == 256) ? XITEM(it) : it; if (item >= 1056 + 528) break;
;     ...
;             if (item < 1056) { const int nx = (G == 256) ? XITEM(it + G) : it + G; gla_pair<false>(kp, l, item, lds, tid, lane, wave, gz0, gz1, gw0, gw1, nx < 1056 ? nx : -1); __syncthreads(); }
;     ...
;             if (item >= 1056) prep_pool_item(kp, l, item - 1056, lds, tid, lane, wave);
.LBB0_258:
	s_and_b32 s17, s44, 0xffffff00
	s_add_i32 s10, s54, s17
	s_and_b64 s[2:3], s[56:57], exec
	s_cselect_b32 s45, s10, s44
	s_cbranch_scc0 .Lm1_noremap
	s_cmpk_lt_i32 s17, 0x500
	s_cbranch_scc1 .Lm1_noremap
	s_cmpk_lt_i32 s54, 32
	s_cbranch_scc1 .Lm1_stop
	s_cmpk_lt_i32 s17, 0x600
	s_cbranch_scc1 .Lm1_noremap
	s_cmpk_gt_i32 s17, 0x600
	s_cbranch_scc1 .Lm1_stop
	s_cmpk_lt_i32 s54, 48
	s_cbranch_scc1 .Lm1_noremap
	s_cmpk_lt_i32 s54, 0x50
	s_cbranch_scc0 .Lm1_setb
	s_add_i32 s45, s54, 0x4d0
	s_branch .Lm1_noremap
.Lm1_setb:
	s_cmpk_lt_i32 s54, 0x70
	s_cbranch_scc0 .Lm1_stop
	s_add_i32 s45, s54, 0x5b0
	s_branch .Lm1_noremap
.Lm1_stop:
	s_movk_i32 s45, 0x7000
.Lm1_noremap:
	s_cmpk_gt_i32 s45, 0x62f
	s_mov_b64 s[2:3], -1
	s_cbranch_scc1 .LBB0_257
	s_cmpk_gt_i32 s45, 0x41f
	s_cbranch_scc1 .LBB0_275
	s_lshl_b32 s10, s45, 1
	s_add_i32 s10, s10, s38
	s_ashr_i32 s13, s10, 2
	s_cmpk_gt_i32 s13, 0x1ff
	s_cbranch_scc0 .LBB0_262
	s_addk_i32 s13, 0xfe00
	s_lshr_b32 s52, s13, 2
	s_bfe_u32 s12, s10, 0x20002
	s_lshl_b32 s2, s52, 8
	s_or_b32 s53, s12, 0x80
	s_add_i32 s11, s2, 0x8000
	s_mov_b64 s[2:3], 0
